# attention loop: selection mask applied on the matrix core (S += A' x B', B' = inverted mask bits as bf16 0/2.0, A' = constant -1.58e29 selector): 1 VALU per score instead of 2, +4 MFMA per tile
# baseline (speedup 1.0000x reference)
; #define SBAR() __builtin_amdgcn_sched_barrier(0)
; __device__ __forceinline__ int v_st(int k, int c) { const int kk = (k & ~0xC) | ((k & 4) << 1) | ((k & 8) >> 1); return ((kk >> 3) * 4 + (c >> 5)) * 512 + ((kk & 7) * 32 + (c & 31)) * 2; }
; __device__ __forceinline__ int v_rd_base(int lane) { return ((lane & 3) << 3) | (((lane >> 2) & 3) << 6) | (((lane >> 4) & 1) << 5) | (((lane >> 5) & 1) << 8); }
; #define SLOAD_H(Kp, Vp, k0) do { S.st_v0 = load8(ROW(Vp, k0, sr)); S.st_v1 = load8(ROW(Vp, k0, 32 + sr));              \
;                          S.st_k0 = load8(ROW(Kp, k0, sr)); S.st_k1 = load8(ROW(Kp, k0, 32 + sr)); } while (0)
; #define SWRITE_HV(bf) do { *(bf16x8*)(V_lds + (bf) * SHM_V + vst0) = S.st_v0; *(bf16x8*)(V_lds + (bf) * SHM_V + vst1) = S.st_v1; } while (0)
; #define MASKT(P0_, P1_) sel_mask_tile(P0_, P1_, mw.x, mw.y, hi)
; __device__ __forceinline__ void attn_block(const BlockRef& cur, const BlockRef& nxt, char* lds, Seam& S) {
;     const int tid = threadIdx.x, wid = __builtin_amdgcn_readfirstlane(tid >> 6), lane = tid & 63, r32 = lane & 31, hi = lane >> 5;
;     const int NT = (cur.P0 + QB - 1) / KVBLK + 1;
;     char* V_lds = lds; char* K_lds = lds + 2 * SHM_V;
;     float* ws = (float*)(lds + 2 * SHM_V + 2 * SHM_K) + wid * 64; float* li_l = ws, * al_l = ws + 32;
;     float m_reg = -1e30f, l_reg = 0; f32x16 o[4] = {};
;     const int sr = tid >> 4, sc = (tid & 15) * 8, vst0 = v_st(sr, sc), vst1 = v_st(32 + sr, sc), kws = KSWZ(sr, sc * 2);
;     const int vb0 = (int)(uintptr_t)V_lds + v_rd_base(lane);
;     const bf16* Kh = cur.K; const bf16* Vh = cur.V;
;     const unsigned mrow_off = (unsigned)(wid * QBLK + r32) * 512u;
;     u32x2 mw;
;     ...
;     constexpr int NQL = 8;
;     ...
;     f32x16 pA0, pA1, pB0, pB1; float mnA, mnB, alA, alB; bf16x8 pa0, pa1, pa2, pa3;
;     SWRITE_HV(0); SBAR();
;     mw = LDMASK(0);
;     if (NT > 1) { SLOAD_H(Kh, Vh, KBASE(1)); }
;     SBAR(); qkt<0>(pA0, pA1, K_lds, r32, hi, S.qr);
;     MASKT(pA0, pA1); partialSM(pA0, pA1, m_reg, mnA, alA);
.LBB0_1298:
	v_readfirstlane_b32 s83, v0
	s_lshr_b32 s12, s38, 6
	s_or_b32 s81, s12, 3
	s_and_b32 s12, s83, 0x3fffffc0
	s_lshl_b32 s12, s12, 2
	s_add_i32 s84, s12, 0
	s_lshr_b32 s12, s83, 1
	s_and_b32 s12, s12, 0x7fffffe0
	v_and_b32_e32 v88, 31, v0
	v_or_b32_e32 v186, s12, v88
	s_mov_b32 s82, 1
	v_lshlrev_b32_e32 v165, 9, v186
	s_add_i32 s84, s84, 0x10000
	s_waitcnt vmcnt(1)
	ds_write_b128 v197, v[130:133]
	s_waitcnt vmcnt(0)
	ds_write_b128 v198, v[134:137]
	v_mov_b32_e32 v183, v167
	v_lshl_add_u64 v[2:3], s[70:71], 0, v[182:183]
	v_mov_b32_e32 v177, v167
	v_mov_b32_e32 v185, v167
	v_lshl_add_u64 v[2:3], v[2:3], 0, v[176:177]
	v_lshl_add_u64 v[4:5], s[70:71], 0, v[184:185]
	global_load_dwordx2 v[86:87], v165, s[68:69]
	v_lshl_add_u64 v[4:5], v[4:5], 0, v[176:177]
	global_load_dwordx4 v[50:53], v[2:3], off
	global_load_dwordx4 v[54:57], v[4:5], off
	v_lshl_add_u64 v[2:3], s[6:7], 0, v[182:183]
	v_lshl_add_u64 v[2:3], v[2:3], 0, v[176:177]
	v_lshl_add_u64 v[4:5], s[6:7], 0, v[184:185]
	v_lshl_add_u64 v[4:5], v[4:5], 0, v[176:177]
	global_load_dwordx4 v[58:61], v[2:3], off
	global_load_dwordx4 v[62:65], v[4:5], off
	ds_read_b128 v[2:5], v199 offset:32768
	ds_read_b128 v[6:9], v199 offset:32896
	s_mov_b32 s36, s13
	s_mov_b32 s37, s13
	s_mov_b32 s38, s13
	s_waitcnt lgkmcnt(1)
	v_mfma_f32_32x32x16_bf16 v[34:49], v[2:5], v[126:129], 0
	ds_read_b128 v[2:5], v199 offset:40960
	ds_read_b128 v[10:13], v199 offset:41088
	s_mov_b32 s39, s13
	s_mov_b32 s40, s13
	s_mov_b32 s41, s13
	s_mov_b32 s42, s13
	s_mov_b32 s43, s13
	s_mov_b32 s44, s13
	s_waitcnt lgkmcnt(1)
	v_mfma_f32_32x32x16_bf16 v[18:33], v[2:5], v[126:129], 0
	ds_read_b128 v[2:5], v200 offset:32768
	ds_read_b128 v[14:17], v200 offset:32896
	s_mov_b32 s45, s13
	s_mov_b32 s46, s13
	s_mov_b32 s47, s13
	s_mov_b32 s48, s13
	s_mov_b32 s49, s13
	s_mov_b32 s50, s13
	s_waitcnt lgkmcnt(1)
	v_mfma_f32_32x32x16_bf16 v[34:49], v[2:5], v[122:125], v[34:49]
	ds_read_b128 v[2:5], v200 offset:40960
	ds_read_b128 v[66:69], v200 offset:41088
	s_mov_b32 s51, s13
	v_lshl_add_u32 v185, v88, 2, s84
	v_lshl_add_u32 v183, v163, 2, s84
	v_lshlrev_b32_e32 v252, 7, v0
	v_and_b32_e32 v252, 0xf800, v252
	v_add_u32_e32 v187, v170, v252
	s_mov_b64 s[16:17], s[70:71]
	s_mov_b64 s[100:101], s[6:7]
	v_mov_b32_e32 v205, 0
	s_waitcnt lgkmcnt(1)
	v_mfma_f32_32x32x16_bf16 v[18:33], v[2:5], v[122:125], v[18:33]
	ds_read_b128 v[2:5], v201 offset:32768
	ds_read_b128 v[70:73], v201 offset:32896
	s_waitcnt lgkmcnt(1)
	v_mfma_f32_32x32x16_bf16 v[34:49], v[2:5], v[118:121], v[34:49]
	ds_read_b128 v[2:5], v201 offset:40960
	ds_read_b128 v[74:77], v201 offset:41088
	s_waitcnt lgkmcnt(1)
	v_mfma_f32_32x32x16_bf16 v[18:33], v[2:5], v[118:121], v[18:33]
	ds_read_b128 v[2:5], v202 offset:32768
	ds_read_b128 v[78:81], v202 offset:32896
	s_waitcnt lgkmcnt(1)
	v_mfma_f32_32x32x16_bf16 v[34:49], v[2:5], v[114:117], v[34:49]
	ds_read_b128 v[2:5], v202 offset:40960
	ds_read_b128 v[82:85], v202 offset:41088
	s_waitcnt vmcnt(0)
	s_waitcnt vmcnt(3)
	ds_write_b128 v197, v[50:53] offset:16384
	s_waitcnt vmcnt(2)
	ds_write_b128 v198, v[54:57] offset:16384
	s_waitcnt vmcnt(1)
	ds_write_b128 v204, v[58:61] offset:49152
	s_waitcnt vmcnt(0)
	ds_write_b128 v204, v[62:65] offset:57344
	s_waitcnt lgkmcnt(0)
	s_barrier
	v_mfma_f32_32x32x16_bf16 v[34:49], v[6:9], v[110:113], v[34:49]
	v_mfma_f32_32x32x16_bf16 v[18:33], v[2:5], v[114:117], v[18:33]
	v_mfma_f32_32x32x16_bf16 v[34:49], v[14:17], v[106:109], v[34:49]
	v_mfma_f32_32x32x16_bf16 v[18:33], v[10:13], v[110:113], v[18:33]
	v_mov_b64_e32 v[2:3], s[36:37]
	v_mov_b64_e32 v[4:5], s[38:39]
	v_mov_b64_e32 v[6:7], s[40:41]
	v_mov_b64_e32 v[8:9], s[42:43]
	v_mov_b64_e32 v[10:11], s[44:45]
	v_mov_b64_e32 v[12:13], s[46:47]
	v_mov_b64_e32 v[14:15], s[48:49]
	v_mfma_f32_32x32x16_bf16 v[34:49], v[70:73], v[102:105], v[34:49]
	v_mov_b64_e32 v[16:17], s[50:51]
	v_mov_b64_e32 v[64:65], v[16:17]
	v_mov_b64_e32 v[62:63], v[14:15]
	v_mov_b64_e32 v[60:61], v[12:13]
	v_mov_b64_e32 v[58:59], v[10:11]
	v_mov_b64_e32 v[56:57], v[8:9]
	v_mov_b64_e32 v[54:55], v[6:7]
	v_mfma_f32_32x32x16_bf16 v[18:33], v[66:69], v[106:109], v[18:33]
	v_lshrrev_b32_e32 v66, v163, v86
	v_bfe_i32 v68, v66, 0, 1
	v_lshrrev_b32_e32 v67, v163, v87
	v_bfe_i32 v69, v67, 0, 1
	v_bfe_i32 v70, v67, 2, 1
	v_bfe_i32 v71, v67, 3, 1
	v_bfe_i32 v72, v67, 8, 1
	v_mfma_f32_32x32x16_bf16 v[34:49], v[78:81], v[98:101], v[34:49]
	v_bfe_i32 v73, v67, 9, 1
	v_bfe_i32 v78, v67, 18, 1
	v_bfe_i32 v79, v67, 19, 1
	v_bfe_i32 v80, v67, 24, 1
	v_bfe_i32 v81, v67, 25, 1
	v_mov_b64_e32 v[52:53], v[4:5]
	v_mov_b64_e32 v[50:51], v[2:3]
	v_mfma_f32_32x32x16_bf16 v[18:33], v[74:77], v[102:105], v[18:33]
	s_nop 3
	v_bitop3_b32 v68, v34, s74, v68 bitop3:0xe4
	v_bfe_i32 v34, v66, 1, 1
	v_bitop3_b32 v35, v35, s74, v34 bitop3:0xe4
	v_bfe_i32 v34, v66, 2, 1
	v_bitop3_b32 v36, v36, s74, v34 bitop3:0xe4
	v_bfe_i32 v34, v66, 3, 1
	v_bitop3_b32 v37, v37, s74, v34 bitop3:0xe4
	v_bfe_i32 v34, v66, 8, 1
	v_bitop3_b32 v38, v38, s74, v34 bitop3:0xe4
	v_bfe_i32 v34, v66, 9, 1
	v_bitop3_b32 v39, v39, s74, v34 bitop3:0xe4
	v_bfe_i32 v34, v66, 10, 1
	v_bitop3_b32 v40, v40, s74, v34 bitop3:0xe4
	v_bfe_i32 v34, v66, 11, 1
	v_mfma_f32_32x32x16_bf16 v[18:33], v[82:85], v[98:101], v[18:33]
	v_bitop3_b32 v41, v41, s74, v34 bitop3:0xe4
	v_bfe_i32 v34, v66, 16, 1
	v_bitop3_b32 v42, v42, s74, v34 bitop3:0xe4
	v_bfe_i32 v34, v66, 17, 1
	v_bitop3_b32 v43, v43, s74, v34 bitop3:0xe4
	v_bfe_i32 v34, v66, 18, 1
	v_bitop3_b32 v44, v44, s74, v34 bitop3:0xe4
	v_bfe_i32 v34, v66, 19, 1
	v_bitop3_b32 v45, v45, s74, v34 bitop3:0xe4
	v_bfe_i32 v34, v66, 24, 1
	v_bitop3_b32 v46, v46, s74, v34 bitop3:0xe4
	v_bfe_i32 v34, v66, 25, 1
; #define SBAR() __builtin_amdgcn_sched_barrier(0)
; #define VMW() asm volatile("s_waitcnt vmcnt(0)" ::: "memory")
; #define SWRITE_H(bf) do { SWRITE_HV(bf); SWRITE_HK(bf); } while (0)
; #define MASKT(P0_, P1_) sel_mask_tile(P0_, P1_, mw.x, mw.y, hi)
; __device__ __forceinline__ void partialSM(f32x16& p0, f32x16& p1, float& m_reg, float& mn, float& alpha) {
;     float pmax = p0[0];
; #pragma unroll
;     for (int r = 1; r < 16; ++r) pmax = fmaxf(pmax, p0[r]);
; #pragma unroll
;     for (int r = 0; r < 16; ++r) pmax = fmaxf(pmax, p1[r]);
;     { auto rr = __builtin_amdgcn_permlane32_swap(__float_as_uint(pmax), __float_as_uint(pmax), false, false);
;       pmax = fmaxf(__uint_as_float(rr[0]), __uint_as_float(rr[1])); }
;     constexpr float C2 = 1.4426950408889634f * SCALE;
;     if (__builtin_expect(__all((pmax - m_reg) * SCALE <= THR), 1)) { mn = m_reg; alpha = 1.f; }
;     else { mn = fmaxf(m_reg, pmax); alpha = __builtin_amdgcn_exp2f((m_reg - mn) * C2); m_reg = mn; }
;     const float mnL = -mn * C2;
; #pragma unroll
;     for (int r = 0; r < 16; ++r) p0[r] = fmaf(p0[r], C2, mnL);
; #pragma unroll
;     for (int r = 0; r < 16; ++r) p1[r] = fmaf(p1[r], C2, mnL);
; #pragma unroll
;     for (int r = 0; r < 16; ++r) p0[r] = __builtin_amdgcn_exp2f(p0[r]);
; }
; __device__ __forceinline__ void attn_block(const BlockRef& cur, const BlockRef& nxt, char* lds, Seam& S) {
;     ...
;     SBAR(); qkt<0>(pA0, pA1, K_lds, r32, hi, S.qr);
;     MASKT(pA0, pA1); partialSM(pA0, pA1, m_reg, mnA, alA);
;     if (NT > 1) { VMW(); SWRITE_H(1); }
;     __syncthreads();
	v_bitop3_b32 v47, v47, s74, v34 bitop3:0xe4
	v_bfe_i32 v34, v66, 26, 1
	v_bitop3_b32 v48, v48, s74, v34 bitop3:0xe4
	v_bfe_i32 v34, v66, 27, 1
	v_bitop3_b32 v18, v18, s74, v69 bitop3:0xe4
	v_bfe_i32 v69, v67, 1, 1
	v_bfe_i32 v74, v67, 10, 1
	v_bfe_i32 v75, v67, 11, 1
	v_bfe_i32 v76, v67, 16, 1
	v_bfe_i32 v77, v67, 17, 1
	v_bfe_i32 v82, v67, 26, 1
	v_bfe_i32 v66, v67, 27, 1
	v_bitop3_b32 v49, v49, s74, v34 bitop3:0xe4
	v_max_f32_e32 v34, v35, v35
	v_max_f32_e32 v67, v68, v68
	v_max_f32_e32 v34, v67, v34
	v_max3_f32 v34, v34, v36, v37
	v_max3_f32 v34, v34, v38, v39
	v_max3_f32 v34, v34, v40, v41
	v_max3_f32 v34, v34, v42, v43
	v_max3_f32 v34, v34, v44, v45
	v_max3_f32 v34, v34, v46, v47
	v_max3_f32 v34, v34, v48, v49
	v_bitop3_b32 v19, v19, s74, v69 bitop3:0xe4
	v_bitop3_b32 v20, v20, s74, v70 bitop3:0xe4
	v_max3_f32 v34, v34, v18, v19
	v_bitop3_b32 v21, v21, s74, v71 bitop3:0xe4
	v_bitop3_b32 v22, v22, s74, v72 bitop3:0xe4
	v_max3_f32 v34, v34, v20, v21
	v_bitop3_b32 v23, v23, s74, v73 bitop3:0xe4
	v_bitop3_b32 v24, v24, s74, v74 bitop3:0xe4
	v_max3_f32 v34, v34, v22, v23
	v_bitop3_b32 v25, v25, s74, v75 bitop3:0xe4
	v_bitop3_b32 v26, v26, s74, v76 bitop3:0xe4
	v_max3_f32 v34, v34, v24, v25
	v_bitop3_b32 v27, v27, s74, v77 bitop3:0xe4
	v_bitop3_b32 v28, v28, s74, v78 bitop3:0xe4
	v_max3_f32 v34, v34, v26, v27
	v_bitop3_b32 v29, v29, s74, v79 bitop3:0xe4
	v_bitop3_b32 v30, v30, s74, v80 bitop3:0xe4
	v_max3_f32 v34, v34, v28, v29
	v_bitop3_b32 v31, v31, s74, v81 bitop3:0xe4
	v_bitop3_b32 v32, v32, s74, v82 bitop3:0xe4
	v_max3_f32 v34, v34, v30, v31
	v_bitop3_b32 v33, v33, s74, v66 bitop3:0xe4
	v_max3_f32 v34, v34, v32, v33
	v_mov_b32_e32 v66, v34
	s_nop 1
	v_permlane32_swap_b32_e32 v34, v66
	v_max_f32_e32 v66, v66, v66
	v_max_f32_e32 v34, v34, v34
	v_max_f32_e32 v34, v34, v66
	v_add_f32_e32 v66, 0x7149f2ca, v34
	v_mul_f32_e32 v66, 0x3db504f3, v66
	v_max_f32_e32 v34, 0xf149f2ca, v34
	v_cmp_ge_f32_e32 vcc, s75, v66
	v_sub_f32_e32 v66, 0xf149f2ca, v34
	v_mul_f32_e32 v66, 0x3e0293ee, v66
	s_cmp_eq_u64 vcc, exec
	v_exp_f32_e32 v66, v66
	s_cselect_b64 vcc, -1, 0
	v_cndmask_b32_e32 v206, v34, v203, vcc
	v_mul_f32_e32 v34, 0xbe0293ee, v206
	v_mov_b32_e32 v67, v34
	v_cndmask_b32_e64 v177, v66, 1.0, vcc
	v_fmamk_f32 v66, v68, 0x3e0293ee, v34
	v_fmamk_f32 v35, v35, 0x3e0293ee, v34
	v_fmamk_f32 v36, v36, 0x3e0293ee, v34
	v_fmamk_f32 v37, v37, 0x3e0293ee, v34
	v_fmamk_f32 v38, v38, 0x3e0293ee, v34
	v_fmamk_f32 v39, v39, 0x3e0293ee, v34
	v_fmamk_f32 v40, v40, 0x3e0293ee, v34
	v_fmamk_f32 v41, v41, 0x3e0293ee, v34
	v_fmamk_f32 v42, v42, 0x3e0293ee, v34
	v_fmamk_f32 v43, v43, 0x3e0293ee, v34
	v_fmamk_f32 v44, v44, 0x3e0293ee, v34
	v_fmamk_f32 v45, v45, 0x3e0293ee, v34
	v_fmamk_f32 v46, v46, 0x3e0293ee, v34
	v_fmamk_f32 v47, v47, 0x3e0293ee, v34
	v_fmamk_f32 v48, v48, 0x3e0293ee, v34
	v_fmac_f32_e32 v67, 0x3e0293ee, v49
	v_exp_f32_e32 v219, v66
	v_exp_f32_e32 v220, v35
	v_exp_f32_e32 v221, v36
	v_exp_f32_e32 v222, v37
	v_exp_f32_e32 v223, v38
	v_exp_f32_e32 v225, v39
	v_exp_f32_e32 v224, v40
	v_exp_f32_e32 v226, v41
	v_exp_f32_e32 v211, v42
	v_exp_f32_e32 v212, v43
	v_exp_f32_e32 v213, v44
	v_exp_f32_e32 v215, v45
	v_exp_f32_e32 v214, v46
	v_exp_f32_e32 v216, v47
	v_exp_f32_e32 v217, v48
	v_exp_f32_e32 v218, v67
	s_lshl_b32 s36, s83, 8
	v_pk_fma_f32 v[152:153], v[32:33], s[14:15], v[34:35] op_sel_hi:[1,0,0]
	v_pk_fma_f32 v[156:157], v[30:31], s[14:15], v[34:35] op_sel_hi:[1,0,0]
	v_pk_fma_f32 v[160:161], v[28:29], s[14:15], v[34:35] op_sel_hi:[1,0,0]
	v_pk_fma_f32 v[150:151], v[26:27], s[14:15], v[34:35] op_sel_hi:[1,0,0]
	v_pk_fma_f32 v[154:155], v[24:25], s[14:15], v[34:35] op_sel_hi:[1,0,0]
	v_pk_fma_f32 v[158:159], v[22:23], s[14:15], v[34:35] op_sel_hi:[1,0,0]
	v_pk_fma_f32 v[192:193], v[20:21], s[14:15], v[34:35] op_sel_hi:[1,0,0]
	v_pk_fma_f32 v[194:195], v[18:19], s[14:15], v[34:35] op_sel_hi:[1,0,0]
	s_and_b32 s36, s36, 0xffffc000
	v_mov_b64_e32 v[48:49], v[16:17]
	v_mov_b64_e32 v[32:33], v[16:17]
	v_and_b32_e32 v254, 31, v0
	v_lshl_or_b32 v254, v254, 9, 16
	v_or_b32_e32 v179, s36, v254
	v_mov_b64_e32 v[46:47], v[14:15]
	v_mov_b64_e32 v[44:45], v[12:13]
	v_mov_b64_e32 v[42:43], v[10:11]
	v_mov_b64_e32 v[40:41], v[8:9]
	v_mov_b64_e32 v[38:39], v[6:7]
	v_mov_b64_e32 v[36:37], v[4:5]
	v_mov_b64_e32 v[34:35], v[2:3]
	v_mov_b64_e32 v[30:31], v[14:15]
	v_mov_b64_e32 v[28:29], v[12:13]
	v_mov_b64_e32 v[26:27], v[10:11]
	v_mov_b64_e32 v[24:25], v[8:9]
	v_mov_b64_e32 v[22:23], v[6:7]
	v_mov_b64_e32 v[20:21], v[4:5]
	v_mov_b64_e32 v[18:19], v[2:3]
	v_and_b32_e32 v130, 63, v0
	v_and_b32_e32 v131, 31, v130
	v_lshrrev_b32_e32 v130, 5, v130
	v_bfe_u32 v132, v131, 2, 1
	v_and_b32_e32 v133, 16, v131
	v_mov_b32_e32 v134, 0xf000
	v_lshlrev_b32_e32 v133, v133, v134
	v_cmp_eq_u32_e32 vcc, v130, v132
	s_nop 1
	v_cndmask_b32_e32 v133, 0, v133, vcc
	v_and_b32_e32 v130, 8, v131
	v_lshrrev_b32_e32 v130, 1, v130
	v_and_or_b32 v130, v131, 3, v130
	v_cmp_eq_u32_e32 vcc, 0, v130
	s_nop 1
	v_cndmask_b32_e32 v188, 0, v133, vcc
	v_cmp_eq_u32_e32 vcc, 1, v130
	s_nop 1
	v_cndmask_b32_e32 v189, 0, v133, vcc
	v_cmp_eq_u32_e32 vcc, 2, v130
	s_nop 1
	v_cndmask_b32_e32 v190, 0, v133, vcc
	v_cmp_eq_u32_e32 vcc, 3, v130
	s_nop 1
	v_cndmask_b32_e32 v191, 0, v133, vcc
	v_cmp_eq_u32_e32 vcc, 4, v130
	s_nop 1
	v_cndmask_b32_e32 v252, 0, v133, vcc
	v_cmp_eq_u32_e32 vcc, 5, v130
	s_nop 1
	v_cndmask_b32_e32 v253, 0, v133, vcc
	v_cmp_eq_u32_e32 vcc, 6, v130
	s_nop 1
	v_cndmask_b32_e32 v254, 0, v133, vcc
	v_cmp_eq_u32_e32 vcc, 7, v130
	s_nop 1
	v_cndmask_b32_e32 v255, 0, v133, vcc
; __device__ __forceinline__ void finishSM(f32x16& p0, f32x16& p1, float alpha, float& l_reg, bf16x8& pa0, bf16x8& pa1, bf16x8& pa2, bf16x8& pa3) {
; #pragma unroll
;     for (int r = 0; r < 16; ++r) p1[r] = __builtin_amdgcn_exp2f(p1[r]);
;     float ps = 0;
; #pragma unroll
;     for (int r = 0; r < 16; ++r) ps += p0[r];
; #pragma unroll
;     for (int r = 0; r < 16; ++r) ps += p1[r];
;     { auto rr = __builtin_amdgcn_permlane32_swap(__float_as_uint(ps), __float_as_uint(ps), false, false);
;       ps = __uint_as_float(rr[0]) + __uint_as_float(rr[1]); }
;     l_reg = l_reg * alpha + ps;
;     ...
;     PK4(p0, 0, pa0); PK4(p0, 8, pa1); PK4(p1, 0, pa2); PK4(p1, 8, pa3);
;     ...
; }
; template <int KB>
; __device__ __forceinline__ void qkt(f32x16& p0, f32x16& p1, const char* K_lds, int r32, int hi, const bf16x8* qr) {
;     p0 = f32x16{}; p1 = f32x16{};
;     const char* kb[4];
; #pragma unroll
;     for (int dd = 0; dd < 4; ++dd) kb[dd] = K_lds + KB * SHM_K + KSWZ(r32, (dd * 16 + hi * 8) * 2);
; #pragma unroll
;     for (int d0 = 0; d0 < 8; ++d0) { const char* a = kb[d0 & 3] + (d0 >> 2) * 128;
;         bf16x8 b0 = *reinterpret_cast<const bf16x8*>(a);
;         bf16x8 b1 = *reinterpret_cast<const bf16x8*>(a + 32 * 256);
;         p0 = __builtin_amdgcn_mfma_f32_32x32x16_bf16(b0, qr[d0], p0, 0, 0, 0);
;         p1 = __builtin_amdgcn_mfma_f32_32x32x16_bf16(b1, qr[d0], p1, 0, 0, 0); }
; }
; template <int VB>
; __device__ __forceinline__ void pv_tile(f32x16* o, int vb0, bf16x8 pa0, bf16x8 pa1, bf16x8 pa2, bf16x8 pa3) {
;     ...
;     PV_D0(0); PV_D0(1); PV_D0(2); PV_D0(3);
;     ...
; }
.LBB0_1299:
	global_load_dwordx2 v[146:147], v179, s[68:69] offset:-8
	s_add_u32 s98, s16, 0x40000
	s_addc_u32 s99, s17, 0
	global_load_dwordx4 v[130:133], v187, s[98:99]
	s_add_u32 s98, s16, 0x50000
	s_addc_u32 s99, s17, 0
	global_load_dwordx4 v[134:137], v187, s[98:99]
	s_add_u32 s98, s100, 0x40000
	s_addc_u32 s99, s101, 0
	global_load_dwordx4 v[138:141], v187, s[98:99]
	s_add_u32 s98, s100, 0x50000
	s_addc_u32 s99, s101, 0
	global_load_dwordx4 v[142:145], v187, s[98:99]
	ds_read_b128 v[66:69], v199 offset:49152
	ds_read_b128 v[82:85], v199 offset:57344
	ds_read_b128 v[172:175], v200 offset:49152
	ds_read_b128 v[232:235], v200 offset:57344
	ds_read_b128 v[236:239], v201 offset:49152
	ds_read_b128 v[240:243], v201 offset:57344
	ds_read_b128 v[244:247], v202 offset:49152
	v_exp_f32_e32 v209, v150
	v_add_f32_e32 v150, v220, v219
	v_add_f32_e32 v150, v221, v150
	s_waitcnt lgkmcnt(6)
	v_mfma_f32_32x32x16_bf16 v[66:81], v[66:69], v[126:129], 0
	v_add_f32_e32 v150, v222, v150
	v_add_f32_e32 v150, v223, v150
	v_add_f32_e32 v150, v225, v150
	v_add_f32_e32 v150, v224, v150
	v_add_f32_e32 v150, v226, v150
	s_waitcnt lgkmcnt(5)
	v_mfma_f32_32x32x16_bf16 v[82:97], v[82:85], v[126:129], 0
	v_add_f32_e32 v150, v211, v150
	v_add_f32_e32 v150, v212, v150
	v_exp_f32_e32 v194, v194
	s_waitcnt lgkmcnt(4)
	v_mfma_f32_32x32x16_bf16 v[66:81], v[172:175], v[122:125], v[66:81]
	ds_read_b128 v[172:175], v202 offset:57344
	v_exp_f32_e32 v195, v195
	v_exp_f32_e32 v192, v192
	v_exp_f32_e32 v193, v193
	s_waitcnt lgkmcnt(4)
	v_mfma_f32_32x32x16_bf16 v[82:97], v[232:235], v[122:125], v[82:97]
	ds_read_b128 v[232:235], v199 offset:49280
	v_exp_f32_e32 v158, v158
	v_exp_f32_e32 v159, v159
	s_waitcnt lgkmcnt(4)
	v_mfma_f32_32x32x16_bf16 v[66:81], v[236:239], v[118:121], v[66:81]
	ds_read_b128 v[236:239], v199 offset:57472
	v_exp_f32_e32 v207, v154
	v_exp_f32_e32 v208, v155
	v_exp_f32_e32 v210, v151
	s_waitcnt lgkmcnt(4)
	v_mfma_f32_32x32x16_bf16 v[82:97], v[240:243], v[118:121], v[82:97]
	ds_read_b128 v[240:243], v200 offset:49280
	v_exp_f32_e32 v160, v160
	v_exp_f32_e32 v161, v161
	s_waitcnt lgkmcnt(4)
	v_mfma_f32_32x32x16_bf16 v[66:81], v[244:247], v[114:117], v[66:81]
	ds_read_b128 v[244:247], v200 offset:57472
	v_exp_f32_e32 v227, v156
	v_cvt_pk_bf16_f32 v151, v224, v226
	v_cvt_pk_bf16_f32 v154, v214, v216
	v_cvt_pk_bf16_f32 v155, v217, v218
	v_cvt_pk_bf16_f32 v156, v194, v195
	s_waitcnt lgkmcnt(4)
	v_mfma_f32_32x32x16_bf16 v[82:97], v[172:175], v[114:117], v[82:97]
	ds_read_b128 v[172:175], v201 offset:49280
	v_exp_f32_e32 v228, v157
	v_exp_f32_e32 v229, v152
	s_waitcnt lgkmcnt(4)
	v_mfma_f32_32x32x16_bf16 v[66:81], v[232:235], v[110:113], v[66:81]
	ds_read_b128 v[232:235], v201 offset:57472
	v_exp_f32_e32 v230, v153
	v_cvt_pk_bf16_f32 v152, v211, v212
	v_cvt_pk_bf16_f32 v153, v213, v215
	v_cvt_pk_bf16_f32 v157, v192, v193
	v_cvt_pk_bf16_f32 v211, v229, v230
	s_waitcnt lgkmcnt(4)
	v_mfma_f32_32x32x16_bf16 v[82:97], v[236:239], v[110:113], v[82:97]
	ds_read_b128 v[236:239], v202 offset:49280
	v_add_f32_e32 v249, v213, v150
	v_add_f32_e32 v249, v215, v249
	v_add_f32_e32 v249, v214, v249
	s_waitcnt lgkmcnt(4)
	v_mfma_f32_32x32x16_bf16 v[66:81], v[240:243], v[106:109], v[66:81]
	ds_read_b128 v[240:243], v202 offset:57472
	v_add_f32_e32 v249, v216, v249
	v_add_f32_e32 v249, v217, v249
	v_add_f32_e32 v249, v218, v249
	v_add_f32_e32 v249, v194, v249
	v_add_f32_e32 v248, v195, v249
	s_waitcnt lgkmcnt(4)
	v_mfma_f32_32x32x16_bf16 v[82:97], v[244:247], v[106:109], v[82:97]
	v_add_f32_e32 v248, v192, v248
	v_add_f32_e32 v248, v193, v248
	v_add_f32_e32 v248, v158, v248
	v_add_f32_e32 v248, v159, v248
	v_add_f32_e32 v248, v207, v248
	s_waitcnt lgkmcnt(3)
	v_mfma_f32_32x32x16_bf16 v[66:81], v[172:175], v[102:105], v[66:81]
	v_add_f32_e32 v248, v208, v248
	v_add_f32_e32 v248, v209, v248
	v_add_f32_e32 v248, v210, v248
	v_add_f32_e32 v248, v160, v248
	v_add_f32_e32 v248, v161, v248
	s_waitcnt lgkmcnt(2)
	v_mfma_f32_32x32x16_bf16 v[82:97], v[232:235], v[102:105], v[82:97]
	v_add_f32_e32 v248, v227, v248
	v_add_f32_e32 v248, v228, v248
	v_add_f32_e32 v248, v229, v248
	v_add_f32_e32 v181, v230, v248
	s_waitcnt lgkmcnt(1)
	v_mfma_f32_32x32x16_bf16 v[66:81], v[236:239], v[98:101], v[66:81]
	v_cvt_pk_bf16_f32 v148, v219, v220
	v_cvt_pk_bf16_f32 v149, v221, v222
	v_cvt_pk_bf16_f32 v150, v223, v225
	v_cvt_pk_bf16_f32 v158, v158, v159
	v_cvt_pk_bf16_f32 v159, v207, v208
	s_waitcnt lgkmcnt(0)
	v_mfma_f32_32x32x16_bf16 v[82:97], v[240:243], v[98:101], v[82:97]
	v_cvt_pk_bf16_f32 v208, v209, v210
	v_cvt_pk_bf16_f32 v210, v227, v228
	v_cvt_pk_bf16_f32 v209, v160, v161
	ds_read_b64_tr_b16 v[172:173], v1 offset:0x0
	ds_read_b64_tr_b16 v[174:175], v1 offset:0x800
	ds_read_b64_tr_b16 v[212:213], v1 offset:0x200
	ds_read_b64_tr_b16 v[214:215], v1 offset:0xa00
	ds_read_b64_tr_b16 v[216:217], v1 offset:0x400
	ds_read_b64_tr_b16 v[218:219], v1 offset:0xc00
	ds_read_b64_tr_b16 v[220:221], v1 offset:0x600
	ds_read_b64_tr_b16 v[222:223], v1 offset:0xe00
	ds_read_b64_tr_b16 v[232:233], v1 offset:0x1000
	ds_read_b64_tr_b16 v[234:235], v1 offset:0x1800
	ds_read_b64_tr_b16 v[236:237], v1 offset:0x1200
	ds_read_b64_tr_b16 v[238:239], v1 offset:0x1a00
	ds_read_b64_tr_b16 v[240:241], v1 offset:0x1400
	ds_read_b64_tr_b16 v[242:243], v1 offset:0x1c00
	s_nop 0
	s_waitcnt lgkmcnt(12)
	v_mfma_f32_32x32x16_bf16 v[2:17], v[148:151], v[172:175], v[2:17]
	ds_read_b64_tr_b16 v[244:245], v1 offset:0x1600
	ds_read_b64_tr_b16 v[246:247], v1 offset:0x1e00
	s_waitcnt vmcnt(4)
	v_not_b32_e32 v160, v146
	v_not_b32_e32 v161, v147
	v_pk_lshrrev_b16 v160, v163, v160 op_sel_hi:[0,1]
	v_pk_lshrrev_b16 v161, v163, v161 op_sel_hi:[0,1]
	s_waitcnt lgkmcnt(12)
; __device__ __forceinline__ void sel_mask_tile(f32x16& p0, f32x16& p1, unsigned wlo, unsigned whi, int hi) {
;     const unsigned NEGB = 0xff800000u;
;     const unsigned lo = wlo >> (4 * hi), h2 = whi >> (4 * hi);
; #pragma unroll
;     for (int r = 0; r < 16; ++r) {
;         const int c = (r & 3) + 8 * (r >> 2);
;         const unsigned m0 = (unsigned)__builtin_amdgcn_sbfe((int)lo, c, 1), m1 = (unsigned)__builtin_amdgcn_sbfe((int)h2, c, 1);
;         p0[r] = __uint_as_float((__float_as_uint(p0[r]) & m0) | (NEGB & ~m0));
;         p1[r] = __uint_as_float((__float_as_uint(p1[r]) & m1) | (NEGB & ~m1));
;     }
; }
; __device__ __forceinline__ void partialSM(f32x16& p0, f32x16& p1, float& m_reg, float& mn, float& alpha) {
;     float pmax = p0[0];
; #pragma unroll
;     for (int r = 1; r < 16; ++r) pmax = fmaxf(pmax, p0[r]);
; #pragma unroll
;     for (int r = 0; r < 16; ++r) pmax = fmaxf(pmax, p1[r]);
;     { auto rr = __builtin_amdgcn_permlane32_swap(__float_as_uint(pmax), __float_as_uint(pmax), false, false);
;       pmax = fmaxf(__uint_as_float(rr[0]), __uint_as_float(rr[1])); }
;     constexpr float C2 = 1.4426950408889634f * SCALE;
;     if (__builtin_expect(__all((pmax - m_reg) * SCALE <= THR), 1)) { mn = m_reg; alpha = 1.f; }
;     else { mn = fmaxf(m_reg, pmax); alpha = __builtin_amdgcn_exp2f((m_reg - mn) * C2); m_reg = mn; }
;     const float mnL = -mn * C2;
; #pragma unroll
;     for (int r = 0; r < 16; ++r) p0[r] = fmaf(p0[r], C2, mnL);
; #pragma unroll
;     for (int r = 0; r < 16; ++r) p1[r] = fmaf(p1[r], C2, mnL);
; #pragma unroll
;     for (int r = 0; r < 16; ++r) p0[r] = __builtin_amdgcn_exp2f(p0[r]);
; }
; template <int VB>
; __device__ __forceinline__ void pv_tile(f32x16* o, int vb0, bf16x8 pa0, bf16x8 pa1, bf16x8 pa2, bf16x8 pa3) {
;     ...
;     PV_D0(0); PV_D0(1); PV_D0(2); PV_D0(3);
;     ...
; }
	v_mfma_f32_32x32x16_bf16 v[50:65], v[148:151], v[212:215], v[50:65]
	ds_read_b64_tr_b16 v[248:249], v1 offset:0x2000
	ds_read_b64_tr_b16 v[250:251], v1 offset:0x2800
	v_and_b32_e32 v224, 0x00010001, v160
	v_pk_lshlrev_b16 v224, 14, v224 op_sel_hi:[0,1]
	v_and_b32_e32 v225, 0x00020002, v160
	v_pk_lshlrev_b16 v225, 13, v225 op_sel_hi:[0,1]
	s_waitcnt lgkmcnt(12)
	v_mfma_f32_32x32x16_bf16 v[34:49], v[148:151], v[216:219], v[34:49]
	ds_read_b64_tr_b16 v[216:217], v1 offset:0x2200
	ds_read_b64_tr_b16 v[218:219], v1 offset:0x2a00
	v_and_b32_e32 v226, 0x00040004, v160
	v_pk_lshlrev_b16 v226, 12, v226 op_sel_hi:[0,1]
	v_and_b32_e32 v227, 0x00080008, v160
	v_pk_lshlrev_b16 v227, 11, v227 op_sel_hi:[0,1]
	s_nop 1
	s_waitcnt lgkmcnt(12)
	v_mfma_f32_32x32x16_bf16 v[18:33], v[148:151], v[220:223], v[18:33]
	ds_read_b64_tr_b16 v[220:221], v1 offset:0x2400
	ds_read_b64_tr_b16 v[222:223], v1 offset:0x2c00
	v_mfma_f32_32x32x16_bf16 v[66:81], v[188:191], v[224:227], v[66:81]
	v_and_b32_e32 v224, 0x01000100, v160
	v_pk_lshlrev_b16 v224, 6, v224 op_sel_hi:[0,1]
	v_and_b32_e32 v225, 0x02000200, v160
	s_waitcnt lgkmcnt(12)
	v_mfma_f32_32x32x16_bf16 v[2:17], v[152:155], v[232:235], v[2:17]
	ds_read_b64_tr_b16 v[232:233], v1 offset:0x2600
	ds_read_b64_tr_b16 v[234:235], v1 offset:0x2e00
	v_pk_lshlrev_b16 v225, 5, v225 op_sel_hi:[0,1]
	v_and_b32_e32 v226, 0x04000400, v160
	v_pk_lshlrev_b16 v226, 4, v226 op_sel_hi:[0,1]
	v_and_b32_e32 v227, 0x08000800, v160
	s_waitcnt lgkmcnt(12)
	v_mfma_f32_32x32x16_bf16 v[50:65], v[152:155], v[236:239], v[50:65]
	ds_read_b64_tr_b16 v[236:237], v1 offset:0x3000
	ds_read_b64_tr_b16 v[238:239], v1 offset:0x3800
	v_pk_lshlrev_b16 v227, 3, v227 op_sel_hi:[0,1]
	s_nop 1
	v_mfma_f32_32x32x16_bf16 v[66:81], v[252:255], v[224:227], v[66:81]
	v_and_b32_e32 v224, 0x00010001, v161
	v_pk_lshlrev_b16 v224, 14, v224 op_sel_hi:[0,1]
	s_waitcnt lgkmcnt(12)
	v_mfma_f32_32x32x16_bf16 v[34:49], v[152:155], v[240:243], v[34:49]
	ds_read_b64_tr_b16 v[240:241], v1 offset:0x3200
	ds_read_b64_tr_b16 v[242:243], v1 offset:0x3a00
	v_and_b32_e32 v225, 0x00020002, v161
	v_pk_lshlrev_b16 v225, 13, v225 op_sel_hi:[0,1]
	v_and_b32_e32 v226, 0x00040004, v161
	v_pk_lshlrev_b16 v226, 12, v226 op_sel_hi:[0,1]
	s_waitcnt lgkmcnt(12)
	v_mfma_f32_32x32x16_bf16 v[18:33], v[152:155], v[244:247], v[18:33]
	ds_read_b64_tr_b16 v[244:245], v1 offset:0x3400
	ds_read_b64_tr_b16 v[246:247], v1 offset:0x3c00
	v_and_b32_e32 v227, 0x00080008, v161
	v_pk_lshlrev_b16 v227, 11, v227 op_sel_hi:[0,1]
	s_nop 1
	v_mfma_f32_32x32x16_bf16 v[82:97], v[188:191], v[224:227], v[82:97]
	v_and_b32_e32 v224, 0x01000100, v161
	s_waitcnt lgkmcnt(12)
	v_mfma_f32_32x32x16_bf16 v[2:17], v[156:159], v[248:251], v[2:17]
	ds_read_b64_tr_b16 v[248:249], v1 offset:0x3600
	ds_read_b64_tr_b16 v[250:251], v1 offset:0x3e00
	v_pk_lshlrev_b16 v224, 6, v224 op_sel_hi:[0,1]
	v_and_b32_e32 v225, 0x02000200, v161
	v_pk_lshlrev_b16 v225, 5, v225 op_sel_hi:[0,1]
	v_and_b32_e32 v226, 0x04000400, v161
	s_waitcnt lgkmcnt(12)
	v_mfma_f32_32x32x16_bf16 v[50:65], v[156:159], v[216:219], v[50:65]
	v_pk_lshlrev_b16 v226, 4, v226 op_sel_hi:[0,1]
	v_and_b32_e32 v227, 0x08000800, v161
	v_pk_lshlrev_b16 v227, 3, v227 op_sel_hi:[0,1]
	s_nop 1
	v_mfma_f32_32x32x16_bf16 v[82:97], v[252:255], v[224:227], v[82:97]
	s_waitcnt lgkmcnt(10)
	v_mfma_f32_32x32x16_bf16 v[34:49], v[156:159], v[220:223], v[34:49]
	s_nop 7
	s_nop 4
	v_max3_f32 v224, v66, v67, v68
	v_max3_f32 v224, v224, v69, v70
	v_max3_f32 v224, v224, v71, v72
	s_waitcnt lgkmcnt(8)
	v_mfma_f32_32x32x16_bf16 v[18:33], v[156:159], v[232:235], v[18:33]
	v_max3_f32 v224, v224, v73, v74
	v_max3_f32 v224, v224, v75, v76
	v_max3_f32 v224, v224, v77, v78
	v_max3_f32 v224, v224, v79, v80
	s_waitcnt lgkmcnt(6)
	v_mfma_f32_32x32x16_bf16 v[2:17], v[208:211], v[236:239], v[2:17]
	v_max3_f32 v224, v224, v81, v82
	v_max3_f32 v224, v224, v83, v84
	v_max3_f32 v224, v224, v85, v86
	v_max3_f32 v224, v224, v87, v88
	s_waitcnt lgkmcnt(4)
	v_mfma_f32_32x32x16_bf16 v[50:65], v[208:211], v[240:243], v[50:65]
	v_max3_f32 v224, v224, v89, v90
	v_max3_f32 v224, v224, v91, v92
	v_max3_f32 v224, v224, v93, v94
	v_max3_f32 v224, v224, v95, v96
	s_waitcnt lgkmcnt(2)
	v_mfma_f32_32x32x16_bf16 v[34:49], v[208:211], v[244:247], v[34:49]
	v_max_f32_e32 v224, v224, v97
	v_mov_b32_e32 v225, v224
	s_nop 1
	v_permlane32_swap_b32_e32 v224, v225
	s_waitcnt lgkmcnt(0)
	v_mfma_f32_32x32x16_bf16 v[18:33], v[208:211], v[248:251], v[18:33]
	s_waitcnt vmcnt(0)
	ds_write_b128 v204, v[138:141] offset:32768
	ds_write_b128 v204, v[142:145] offset:40960
	v_max_f32_e32 v224, v224, v225
	v_sub_f32_e32 v225, v224, v206
	v_mul_f32_e32 v225, 0x3db504f3, v225
	v_cmp_ge_f32_e32 vcc, s75, v225
	s_cmp_eq_u64 vcc, exec
	s_cselect_b64 s[6:7], -1, 0
	s_cbranch_scc1 .Lp5_b1fast
	v_max_f32_e32 v224, v206, v224
	v_sub_f32_e32 v226, v206, v224
	v_mul_f32_e32 v226, 0x3e0293ee, v226
	v_exp_f32_e32 v226, v226
; #define SBAR() __builtin_amdgcn_sched_barrier(0)
; #define VMW() asm volatile("s_waitcnt vmcnt(0)" ::: "memory")
; #define SLOAD_H(Kp, Vp, k0) do { S.st_v0 = load8(ROW(Vp, k0, sr)); S.st_v1 = load8(ROW(Vp, k0, 32 + sr));              \
;                          S.st_k0 = load8(ROW(Kp, k0, sr)); S.st_k1 = load8(ROW(Kp, k0, 32 + sr)); } while (0)
; #define SWRITE_HV(bf) do { *(bf16x8*)(V_lds + (bf) * SHM_V + vst0) = S.st_v0; *(bf16x8*)(V_lds + (bf) * SHM_V + vst1) = S.st_v1; } while (0)
; #define SWRITE_H(bf) do { SWRITE_HV(bf); SWRITE_HK(bf); } while (0)
; #define MASKT(P0_, P1_) sel_mask_tile(P0_, P1_, mw.x, mw.y, hi)
; __device__ __forceinline__ void partialSM(f32x16& p0, f32x16& p1, float& m_reg, float& mn, float& alpha) {
;     ...
;     constexpr float C2 = 1.4426950408889634f * SCALE;
;     if (__builtin_expect(__all((pmax - m_reg) * SCALE <= THR), 1)) { mn = m_reg; alpha = 1.f; }
;     else { mn = fmaxf(m_reg, pmax); alpha = __builtin_amdgcn_exp2f((m_reg - mn) * C2); m_reg = mn; }
;     const float mnL = -mn * C2;
; #pragma unroll
;     for (int r = 0; r < 16; ++r) p0[r] = fmaf(p0[r], C2, mnL);
; #pragma unroll
;     for (int r = 0; r < 16; ++r) p1[r] = fmaf(p1[r], C2, mnL);
; #pragma unroll
;     for (int r = 0; r < 16; ++r) p0[r] = __builtin_amdgcn_exp2f(p0[r]);
; __device__ __forceinline__ void attn_block(const BlockRef& cur, const BlockRef& nxt, char* lds, Seam& S) {
;     ...
;     constexpr int NQL = 8;
;     ...
;     f32x16 pA0, pA1, pB0, pB1; float mnA, mnB, alA, alB; bf16x8 pa0, pa1, pa2, pa3;
;     SWRITE_HV(0); SBAR();
;     mw = LDMASK(0);
;     if (NT > 1) { SLOAD_H(Kh, Vh, KBASE(1)); }
;     SBAR(); qkt<0>(pA0, pA1, K_lds, r32, hi, S.qr);
;     MASKT(pA0, pA1); partialSM(pA0, pA1, m_reg, mnA, alA);
;     if (NT > 1) { VMW(); SWRITE_H(1); }
;     __syncthreads();
.Lp5_b1fast:
	s_barrier
	s_waitcnt vmcnt(0)
	v_cndmask_b32_e64 v208, v226, 1.0, s[6:7]
	s_not_b64 vcc, s[6:7]
	ds_write_b128 v197, v[130:133]
	ds_write_b128 v198, v[134:137]
	s_cbranch_vccz .LBB0_1303
	s_and_saveexec_b64 s[36:37], s[0:1]
	ds_write_b32 v185, v208 offset:128
	s_or_b64 exec, exec, s[36:37]
	s_waitcnt lgkmcnt(0)
	ds_read_b128 v[150:153], v183 offset:224
	ds_read_b128 v[154:157], v183 offset:192
	ds_read_b128 v[158:161], v183 offset:160
	ds_read_b128 v[172:175], v183 offset:128
	s_waitcnt lgkmcnt(3)
	v_pk_mul_f32 v[16:17], v[16:17], v[152:153]
	s_waitcnt lgkmcnt(2)
	v_pk_mul_f32 v[12:13], v[12:13], v[156:157]
	s_waitcnt lgkmcnt(1)
	v_pk_mul_f32 v[8:9], v[8:9], v[160:161]
	s_waitcnt lgkmcnt(0)
	v_pk_mul_f32 v[4:5], v[4:5], v[174:175]
	v_pk_mul_f32 v[14:15], v[14:15], v[150:151]
	v_pk_mul_f32 v[10:11], v[10:11], v[154:155]
	v_pk_mul_f32 v[6:7], v[6:7], v[158:159]
	v_pk_mul_f32 v[2:3], v[2:3], v[172:173]
	v_pk_mul_f32 v[64:65], v[64:65], v[152:153]
	v_pk_mul_f32 v[60:61], v[60:61], v[156:157]
	v_pk_mul_f32 v[56:57], v[56:57], v[160:161]
	v_pk_mul_f32 v[52:53], v[52:53], v[174:175]
	v_pk_mul_f32 v[62:63], v[62:63], v[150:151]
	v_pk_mul_f32 v[58:59], v[58:59], v[154:155]
	v_pk_mul_f32 v[54:55], v[54:55], v[158:159]
	v_pk_mul_f32 v[50:51], v[50:51], v[172:173]
	v_pk_mul_f32 v[48:49], v[48:49], v[152:153]
	v_pk_mul_f32 v[44:45], v[44:45], v[156:157]
	v_pk_mul_f32 v[40:41], v[40:41], v[160:161]
	v_pk_mul_f32 v[36:37], v[36:37], v[174:175]
	v_pk_mul_f32 v[46:47], v[46:47], v[150:151]
	v_pk_mul_f32 v[42:43], v[42:43], v[154:155]
	v_pk_mul_f32 v[38:39], v[38:39], v[158:159]
	v_pk_mul_f32 v[34:35], v[34:35], v[172:173]
	v_pk_mul_f32 v[32:33], v[32:33], v[152:153]
	v_pk_mul_f32 v[28:29], v[28:29], v[156:157]
	v_pk_mul_f32 v[24:25], v[24:25], v[160:161]
	v_pk_mul_f32 v[20:21], v[20:21], v[174:175]
	v_pk_mul_f32 v[30:31], v[30:31], v[150:151]
	v_pk_mul_f32 v[26:27], v[26:27], v[154:155]
	v_pk_mul_f32 v[22:23], v[22:23], v[158:159]
	v_pk_mul_f32 v[18:19], v[18:19], v[172:173]
.LBB0_1303:
	v_cndmask_b32_e64 v206, v224, v206, s[6:7]
	v_mul_f32_e32 v207, 0xbe0293ee, v206
	v_fmamk_f32 v146, v66, 0x3e0293ee, v207
	v_fmamk_f32 v147, v67, 0x3e0293ee, v207
	v_fmamk_f32 v148, v68, 0x3e0293ee, v207
	v_fmamk_f32 v159, v69, 0x3e0293ee, v207
	v_fmamk_f32 v160, v70, 0x3e0293ee, v207
	v_fmamk_f32 v161, v71, 0x3e0293ee, v207
	v_fmamk_f32 v149, v72, 0x3e0293ee, v207
	v_fmamk_f32 v158, v73, 0x3e0293ee, v207
	v_fmamk_f32 v150, v74, 0x3e0293ee, v207
	v_fmamk_f32 v151, v75, 0x3e0293ee, v207
	v_fmamk_f32 v155, v76, 0x3e0293ee, v207
	v_fmamk_f32 v157, v77, 0x3e0293ee, v207
	v_fmamk_f32 v152, v78, 0x3e0293ee, v207
	v_fmamk_f32 v153, v79, 0x3e0293ee, v207
	v_fmamk_f32 v154, v80, 0x3e0293ee, v207
	v_fmamk_f32 v156, v81, 0x3e0293ee, v207
	v_exp_f32_e32 v146, v146
	v_exp_f32_e32 v147, v147
	v_exp_f32_e32 v148, v148
	v_exp_f32_e32 v159, v159
	v_exp_f32_e32 v160, v160
	v_exp_f32_e32 v161, v161
	v_exp_f32_e32 v149, v149
	v_exp_f32_e32 v158, v158
	v_exp_f32_e32 v150, v150
	v_exp_f32_e32 v151, v151
	v_exp_f32_e32 v155, v155
	v_exp_f32_e32 v157, v157
	v_exp_f32_e32 v152, v152
	v_exp_f32_e32 v153, v153
	v_exp_f32_e32 v154, v154
	v_exp_f32_e32 v156, v156
	v_fmamk_f32 v210, v87, 0x3e0293ee, v207
	v_fmamk_f32 v209, v94, 0x3e0293ee, v207
	v_fmamk_f32 v217, v82, 0x3e0293ee, v207
	v_fmamk_f32 v218, v83, 0x3e0293ee, v207
	v_fmamk_f32 v219, v84, 0x3e0293ee, v207
	v_fmamk_f32 v220, v85, 0x3e0293ee, v207
	v_fmamk_f32 v221, v86, 0x3e0293ee, v207
	v_fmamk_f32 v211, v88, 0x3e0293ee, v207
	v_fmamk_f32 v212, v89, 0x3e0293ee, v207
	v_fmamk_f32 v213, v90, 0x3e0293ee, v207
	v_fmamk_f32 v214, v91, 0x3e0293ee, v207
	v_fmamk_f32 v215, v92, 0x3e0293ee, v207
	v_fmamk_f32 v216, v93, 0x3e0293ee, v207
	v_fmamk_f32 v222, v95, 0x3e0293ee, v207
	v_fmamk_f32 v223, v96, 0x3e0293ee, v207
	v_fmac_f32_e32 v207, 0x3e0293ee, v97
	s_waitcnt lgkmcnt(0)
	s_barrier
	global_load_dwordx2 v[228:229], v179, s[68:69]
	s_add_i32 s98, s82, 2
	s_cmp_gt_u32 s98, s81
	s_cbranch_scc1 .Lp5_a2
	s_add_u32 s98, s16, 0x60000
	s_addc_u32 s99, s17, 0
	global_load_dwordx4 v[130:133], v187, s[98:99]
	s_add_u32 s98, s16, 0x70000
	s_addc_u32 s99, s17, 0
	global_load_dwordx4 v[134:137], v187, s[98:99]
	s_add_u32 s98, s100, 0x60000
	s_addc_u32 s99, s101, 0
	global_load_dwordx4 v[138:141], v187, s[98:99]
	s_add_u32 s98, s100, 0x70000
	s_addc_u32 s99, s101, 0
	global_load_dwordx4 v[142:145], v187, s[98:99]

; __device__ __forceinline__ void sel_mask_tile(f32x16& p0, f32x16& p1, unsigned wlo, unsigned whi, int hi) {
;     const unsigned NEGB = 0xff800000u;
;     const unsigned lo = wlo >> (4 * hi), h2 = whi >> (4 * hi);
; #pragma unroll
;     for (int r = 0; r < 16; ++r) {
;         const int c = (r & 3) + 8 * (r >> 2);
;         const unsigned m0 = (unsigned)__builtin_amdgcn_sbfe((int)lo, c, 1), m1 = (unsigned)__builtin_amdgcn_sbfe((int)h2, c, 1);
;         p0[r] = __uint_as_float((__float_as_uint(p0[r]) & m0) | (NEGB & ~m0));
;         p1[r] = __uint_as_float((__float_as_uint(p1[r]) & m1) | (NEGB & ~m1));
;     }
; }
; __device__ __forceinline__ void partialSM(f32x16& p0, f32x16& p1, float& m_reg, float& mn, float& alpha) {
;     float pmax = p0[0];
; #pragma unroll
;     for (int r = 1; r < 16; ++r) pmax = fmaxf(pmax, p0[r]);
; #pragma unroll
;     for (int r = 0; r < 16; ++r) pmax = fmaxf(pmax, p1[r]);
;     { auto rr = __builtin_amdgcn_permlane32_swap(__float_as_uint(pmax), __float_as_uint(pmax), false, false);
;       pmax = fmaxf(__uint_as_float(rr[0]), __uint_as_float(rr[1])); }
; template <int VB>
; __device__ __forceinline__ void pv_tile(f32x16* o, int vb0, bf16x8 pa0, bf16x8 pa1, bf16x8 pa2, bf16x8 pa3) {
;     ...
;     PV_D0(0); PV_D0(1); PV_D0(2); PV_D0(3);
;     ...
; }
.LBB0_1305:
	ds_read_b64_tr_b16 v[212:213], v1 offset:0x4000
	ds_read_b64_tr_b16 v[214:215], v1 offset:0x4800
	ds_read_b64_tr_b16 v[216:217], v1 offset:0x4200
	ds_read_b64_tr_b16 v[218:219], v1 offset:0x4a00
	ds_read_b64_tr_b16 v[220:221], v1 offset:0x4400
	ds_read_b64_tr_b16 v[222:223], v1 offset:0x4c00
	ds_read_b64_tr_b16 v[232:233], v1 offset:0x4600
	ds_read_b64_tr_b16 v[234:235], v1 offset:0x4e00
	ds_read_b64_tr_b16 v[236:237], v1 offset:0x5000
	ds_read_b64_tr_b16 v[238:239], v1 offset:0x5800
	ds_read_b64_tr_b16 v[240:241], v1 offset:0x5200
	ds_read_b64_tr_b16 v[242:243], v1 offset:0x5a00
	ds_read_b64_tr_b16 v[244:245], v1 offset:0x5400
	ds_read_b64_tr_b16 v[246:247], v1 offset:0x5c00
	s_nop 0
	s_waitcnt lgkmcnt(12)
	v_mfma_f32_32x32x16_bf16 v[2:17], v[146:149], v[212:215], v[2:17]
	ds_read_b64_tr_b16 v[248:249], v1 offset:0x5600
	ds_read_b64_tr_b16 v[250:251], v1 offset:0x5e00
	s_waitcnt vmcnt(4)
	v_not_b32_e32 v193, v228
	v_not_b32_e32 v194, v229
	v_pk_lshrrev_b16 v193, v163, v193 op_sel_hi:[0,1]
	v_pk_lshrrev_b16 v194, v163, v194 op_sel_hi:[0,1]
	s_waitcnt lgkmcnt(12)
	v_mfma_f32_32x32x16_bf16 v[50:65], v[146:149], v[216:219], v[50:65]
	ds_read_b64_tr_b16 v[216:217], v1 offset:0x6000
	ds_read_b64_tr_b16 v[218:219], v1 offset:0x6800
	v_and_b32_e32 v224, 0x00010001, v194
	v_pk_lshlrev_b16 v224, 14, v224 op_sel_hi:[0,1]
	v_and_b32_e32 v225, 0x00020002, v194
	v_pk_lshlrev_b16 v225, 13, v225 op_sel_hi:[0,1]
	s_waitcnt lgkmcnt(12)
	v_mfma_f32_32x32x16_bf16 v[34:49], v[146:149], v[220:223], v[34:49]
	ds_read_b64_tr_b16 v[220:221], v1 offset:0x6200
	ds_read_b64_tr_b16 v[222:223], v1 offset:0x6a00
	v_and_b32_e32 v226, 0x00040004, v194
	v_pk_lshlrev_b16 v226, 12, v226 op_sel_hi:[0,1]
	v_and_b32_e32 v227, 0x00080008, v194
	v_pk_lshlrev_b16 v227, 11, v227 op_sel_hi:[0,1]
	s_nop 1
	s_waitcnt lgkmcnt(12)
	v_mfma_f32_32x32x16_bf16 v[18:33], v[146:149], v[232:235], v[18:33]
	ds_read_b64_tr_b16 v[232:233], v1 offset:0x6400
	ds_read_b64_tr_b16 v[234:235], v1 offset:0x6c00
	v_mfma_f32_32x32x16_bf16 v[66:81], v[188:191], v[224:227], v[66:81]
	v_and_b32_e32 v224, 0x01000100, v194
	v_pk_lshlrev_b16 v224, 6, v224 op_sel_hi:[0,1]
	v_and_b32_e32 v225, 0x02000200, v194
	s_waitcnt lgkmcnt(12)
	v_mfma_f32_32x32x16_bf16 v[2:17], v[150:153], v[236:239], v[2:17]
	ds_read_b64_tr_b16 v[236:237], v1 offset:0x6600
	ds_read_b64_tr_b16 v[238:239], v1 offset:0x6e00
	v_pk_lshlrev_b16 v225, 5, v225 op_sel_hi:[0,1]
	v_and_b32_e32 v226, 0x04000400, v194
	v_pk_lshlrev_b16 v226, 4, v226 op_sel_hi:[0,1]
	v_and_b32_e32 v227, 0x08000800, v194
	s_waitcnt lgkmcnt(12)
	v_mfma_f32_32x32x16_bf16 v[50:65], v[150:153], v[240:243], v[50:65]
	ds_read_b64_tr_b16 v[240:241], v1 offset:0x7000
	ds_read_b64_tr_b16 v[242:243], v1 offset:0x7800
	v_pk_lshlrev_b16 v227, 3, v227 op_sel_hi:[0,1]
	s_nop 1
	v_mfma_f32_32x32x16_bf16 v[66:81], v[252:255], v[224:227], v[66:81]
	v_and_b32_e32 v224, 0x00010001, v193
	v_pk_lshlrev_b16 v224, 14, v224 op_sel_hi:[0,1]
	s_waitcnt lgkmcnt(12)
	v_mfma_f32_32x32x16_bf16 v[34:49], v[150:153], v[244:247], v[34:49]
	ds_read_b64_tr_b16 v[244:245], v1 offset:0x7200
	ds_read_b64_tr_b16 v[246:247], v1 offset:0x7a00
	v_and_b32_e32 v225, 0x00020002, v193
	v_pk_lshlrev_b16 v225, 13, v225 op_sel_hi:[0,1]
	v_and_b32_e32 v226, 0x00040004, v193
	v_pk_lshlrev_b16 v226, 12, v226 op_sel_hi:[0,1]
	s_waitcnt lgkmcnt(12)
	v_mfma_f32_32x32x16_bf16 v[18:33], v[150:153], v[248:251], v[18:33]
	ds_read_b64_tr_b16 v[248:249], v1 offset:0x7400
	ds_read_b64_tr_b16 v[250:251], v1 offset:0x7c00
	v_and_b32_e32 v227, 0x00080008, v193
	v_pk_lshlrev_b16 v227, 11, v227 op_sel_hi:[0,1]
	s_nop 1
	v_mfma_f32_32x32x16_bf16 v[82:97], v[188:191], v[224:227], v[82:97]
	v_and_b32_e32 v224, 0x01000100, v193
	s_waitcnt lgkmcnt(12)
	v_mfma_f32_32x32x16_bf16 v[2:17], v[154:157], v[216:219], v[2:17]
	ds_read_b64_tr_b16 v[216:217], v1 offset:0x7600
	ds_read_b64_tr_b16 v[218:219], v1 offset:0x7e00
	v_pk_lshlrev_b16 v224, 6, v224 op_sel_hi:[0,1]
	v_and_b32_e32 v225, 0x02000200, v193
	v_pk_lshlrev_b16 v225, 5, v225 op_sel_hi:[0,1]
	v_and_b32_e32 v226, 0x04000400, v193
	s_waitcnt lgkmcnt(12)
	v_mfma_f32_32x32x16_bf16 v[50:65], v[154:157], v[220:223], v[50:65]
	v_pk_lshlrev_b16 v226, 4, v226 op_sel_hi:[0,1]
	v_and_b32_e32 v227, 0x08000800, v193
	v_pk_lshlrev_b16 v227, 3, v227 op_sel_hi:[0,1]
	s_nop 1
	v_mfma_f32_32x32x16_bf16 v[82:97], v[252:255], v[224:227], v[82:97]
	s_waitcnt lgkmcnt(10)
	v_mfma_f32_32x32x16_bf16 v[34:49], v[154:157], v[232:235], v[34:49]
	s_nop 7
	s_nop 4
	v_max3_f32 v224, v66, v67, v68
	v_max3_f32 v224, v224, v69, v70
	v_max3_f32 v224, v224, v71, v72
	s_waitcnt lgkmcnt(8)
	v_mfma_f32_32x32x16_bf16 v[18:33], v[154:157], v[236:239], v[18:33]
	v_max3_f32 v224, v224, v73, v74
	v_max3_f32 v224, v224, v75, v76
	v_max3_f32 v224, v224, v77, v78
	v_max3_f32 v224, v224, v79, v80
	s_waitcnt lgkmcnt(6)
	v_mfma_f32_32x32x16_bf16 v[2:17], v[158:161], v[240:243], v[2:17]
	v_max3_f32 v224, v224, v81, v82
	v_max3_f32 v224, v224, v83, v84
	v_max3_f32 v224, v224, v85, v86
	v_max3_f32 v224, v224, v87, v88
	s_waitcnt lgkmcnt(4)
	v_mfma_f32_32x32x16_bf16 v[50:65], v[158:161], v[244:247], v[50:65]
	v_max3_f32 v224, v224, v89, v90
	v_max3_f32 v224, v224, v91, v92
	v_max3_f32 v224, v224, v93, v94
	v_max3_f32 v224, v224, v95, v96
	s_waitcnt lgkmcnt(2)
	v_mfma_f32_32x32x16_bf16 v[34:49], v[158:161], v[248:251], v[34:49]
	v_max_f32_e32 v224, v224, v97
	v_mov_b32_e32 v225, v224
	s_nop 1
	v_permlane32_swap_b32_e32 v224, v225
	s_waitcnt lgkmcnt(0)
	v_mfma_f32_32x32x16_bf16 v[18:33], v[158:161], v[216:219], v[18:33]
	s_cmp_eq_u64 s[36:37], 0
	s_cbranch_scc1 .Lp5_kw2_skip
	s_waitcnt vmcnt(0)
	ds_write_b128 v204, v[138:141] offset:49152
	ds_write_b128 v204, v[142:145] offset:57344
; #define SBAR() __builtin_amdgcn_sched_barrier(0)
; #define VMW() asm volatile("s_waitcnt vmcnt(0)" ::: "memory")
; #define SLOAD_H(Kp, Vp, k0) do { S.st_v0 = load8(ROW(Vp, k0, sr)); S.st_v1 = load8(ROW(Vp, k0, 32 + sr));              \
;                          S.st_k0 = load8(ROW(Kp, k0, sr)); S.st_k1 = load8(ROW(Kp, k0, 32 + sr)); } while (0)
; #define SWRITE_HV(bf) do { *(bf16x8*)(V_lds + (bf) * SHM_V + vst0) = S.st_v0; *(bf16x8*)(V_lds + (bf) * SHM_V + vst1) = S.st_v1; } while (0)
; #define SWRITE_H(bf) do { SWRITE_HV(bf); SWRITE_HK(bf); } while (0)
; #define MASKT(P0_, P1_) sel_mask_tile(P0_, P1_, mw.x, mw.y, hi)
; __device__ __forceinline__ void partialSM(f32x16& p0, f32x16& p1, float& m_reg, float& mn, float& alpha) {
;     ...
;     { auto rr = __builtin_amdgcn_permlane32_swap(__float_as_uint(pmax), __float_as_uint(pmax), false, false);
;       pmax = fmaxf(__uint_as_float(rr[0]), __uint_as_float(rr[1])); }
;     constexpr float C2 = 1.4426950408889634f * SCALE;
;     if (__builtin_expect(__all((pmax - m_reg) * SCALE <= THR), 1)) { mn = m_reg; alpha = 1.f; }
;     else { mn = fmaxf(m_reg, pmax); alpha = __builtin_amdgcn_exp2f((m_reg - mn) * C2); m_reg = mn; }
;     const float mnL = -mn * C2;
; #pragma unroll
;     for (int r = 0; r < 16; ++r) p0[r] = fmaf(p0[r], C2, mnL);
; #pragma unroll
;     for (int r = 0; r < 16; ++r) p1[r] = fmaf(p1[r], C2, mnL);
; #pragma unroll
;     for (int r = 0; r < 16; ++r) p0[r] = __builtin_amdgcn_exp2f(p0[r]);
; __device__ __forceinline__ void attn_block(const BlockRef& cur, const BlockRef& nxt, char* lds, Seam& S) {
;     ...
;     constexpr int NQL = 8;
;     ...
;     f32x16 pA0, pA1, pB0, pB1; float mnA, mnB, alA, alB; bf16x8 pa0, pa1, pa2, pa3;
;     SWRITE_HV(0); SBAR();
;     mw = LDMASK(0);
;     if (NT > 1) { SLOAD_H(Kh, Vh, KBASE(1)); }
;     SBAR(); qkt<0>(pA0, pA1, K_lds, r32, hi, S.qr);
;     MASKT(pA0, pA1); partialSM(pA0, pA1, m_reg, mnA, alA);
;     if (NT > 1) { VMW(); SWRITE_H(1); }
;     __syncthreads();
;     ...
;     for (int t = 1; t + 1 < NT; t += 2) {
;         HALF_STEP(pB0, pB1, mnB, alB, pA0, pA1, alA, t, 1, 0, 0);
;         HALF_STEP(pA0, pA1, mnA, alA, pB0, pB1, alB, t + 1, 0, 1, 1);
;     }
.Lp5_kw2_skip:
	v_max_f32_e32 v224, v224, v225
	v_sub_f32_e32 v225, v224, v206
	v_mul_f32_e32 v225, 0x3db504f3, v225
	v_cmp_ge_f32_e32 vcc, s75, v225
	s_cmp_eq_u64 vcc, exec
	s_cselect_b64 s[6:7], -1, 0
	s_andn2_b64 vcc, exec, s[36:37]
	s_barrier
	s_cbranch_vccnz .LBB0_1307
	s_waitcnt vmcnt(0)
	ds_write_b128 v197, v[130:133] offset:16384
	ds_write_b128 v198, v[134:137] offset:16384
.LBB0_1307:
	v_mov_b32_e32 v207, 1.0
	s_not_b64 vcc, s[6:7]
	s_cbranch_vccz .LBB0_1311
	v_max_f32_e32 v224, v206, v224
	v_sub_f32_e32 v225, v206, v224
	v_mul_f32_e32 v225, 0x3e0293ee, v225
	v_exp_f32_e32 v225, v225
	s_nop 0
	v_cndmask_b32_e64 v207, v225, 1.0, s[6:7]
	s_and_saveexec_b64 s[36:37], s[0:1]
	ds_write_b32 v185, v207 offset:128
	s_or_b64 exec, exec, s[36:37]
	s_waitcnt lgkmcnt(0)
	ds_read_b128 v[236:239], v183 offset:224
	ds_read_b128 v[130:133], v183 offset:192
	ds_read_b128 v[134:137], v183 offset:160
	ds_read_b128 v[138:141], v183 offset:128
	s_waitcnt lgkmcnt(3)
	v_pk_mul_f32 v[16:17], v[16:17], v[238:239]
	s_waitcnt lgkmcnt(2)
	v_pk_mul_f32 v[12:13], v[12:13], v[132:133]
	s_waitcnt lgkmcnt(1)
	v_pk_mul_f32 v[8:9], v[8:9], v[136:137]
	s_waitcnt lgkmcnt(0)
	v_pk_mul_f32 v[4:5], v[4:5], v[140:141]
	v_pk_mul_f32 v[14:15], v[14:15], v[236:237]
	v_pk_mul_f32 v[10:11], v[10:11], v[130:131]
	v_pk_mul_f32 v[6:7], v[6:7], v[134:135]
	v_pk_mul_f32 v[2:3], v[2:3], v[138:139]
	v_pk_mul_f32 v[64:65], v[64:65], v[238:239]
	v_pk_mul_f32 v[60:61], v[60:61], v[132:133]
	v_pk_mul_f32 v[56:57], v[56:57], v[136:137]
	v_pk_mul_f32 v[52:53], v[52:53], v[140:141]
	v_pk_mul_f32 v[62:63], v[62:63], v[236:237]
	v_pk_mul_f32 v[58:59], v[58:59], v[130:131]
	v_pk_mul_f32 v[54:55], v[54:55], v[134:135]
	v_pk_mul_f32 v[50:51], v[50:51], v[138:139]
	v_pk_mul_f32 v[48:49], v[48:49], v[238:239]
	v_pk_mul_f32 v[44:45], v[44:45], v[132:133]
	v_pk_mul_f32 v[40:41], v[40:41], v[136:137]
	v_pk_mul_f32 v[36:37], v[36:37], v[140:141]
	v_pk_mul_f32 v[46:47], v[46:47], v[236:237]
	v_pk_mul_f32 v[42:43], v[42:43], v[130:131]
	v_pk_mul_f32 v[38:39], v[38:39], v[134:135]
	v_pk_mul_f32 v[34:35], v[34:35], v[138:139]
	v_pk_mul_f32 v[32:33], v[32:33], v[238:239]
	v_pk_mul_f32 v[28:29], v[28:29], v[132:133]
	v_pk_mul_f32 v[24:25], v[24:25], v[136:137]
	v_pk_mul_f32 v[20:21], v[20:21], v[140:141]
	v_pk_mul_f32 v[30:31], v[30:31], v[236:237]
	v_pk_mul_f32 v[26:27], v[26:27], v[130:131]
	v_pk_mul_f32 v[22:23], v[22:23], v[134:135]
	v_pk_mul_f32 v[18:19], v[18:19], v[138:139]
.LBB0_1311:
	v_cndmask_b32_e64 v206, v224, v206, s[6:7]
	v_mul_f32_e32 v232, 0xbe0293ee, v206
	v_fmamk_f32 v219, v82, 0x3e0293ee, v232
	v_fmamk_f32 v220, v83, 0x3e0293ee, v232
	v_fmamk_f32 v221, v84, 0x3e0293ee, v232
	v_fmamk_f32 v222, v85, 0x3e0293ee, v232
	v_fmamk_f32 v223, v86, 0x3e0293ee, v232
	v_fmamk_f32 v225, v87, 0x3e0293ee, v232
	v_fmamk_f32 v224, v88, 0x3e0293ee, v232
	v_fmamk_f32 v226, v89, 0x3e0293ee, v232
	v_fmamk_f32 v211, v90, 0x3e0293ee, v232
	v_fmamk_f32 v212, v91, 0x3e0293ee, v232
	v_fmamk_f32 v213, v92, 0x3e0293ee, v232
	v_fmamk_f32 v215, v93, 0x3e0293ee, v232
	v_fmamk_f32 v214, v94, 0x3e0293ee, v232
	v_fmamk_f32 v216, v95, 0x3e0293ee, v232
	v_fmamk_f32 v217, v96, 0x3e0293ee, v232
	v_fmamk_f32 v218, v97, 0x3e0293ee, v232
	v_exp_f32_e32 v219, v219
	v_exp_f32_e32 v220, v220
	v_exp_f32_e32 v221, v221
	v_exp_f32_e32 v222, v222
	v_exp_f32_e32 v223, v223
	v_exp_f32_e32 v225, v225
	v_exp_f32_e32 v224, v224
	v_exp_f32_e32 v226, v226
	v_exp_f32_e32 v211, v211
	v_exp_f32_e32 v212, v212
	v_exp_f32_e32 v213, v213
	v_exp_f32_e32 v215, v215
	v_exp_f32_e32 v214, v214
	v_exp_f32_e32 v216, v216
	v_exp_f32_e32 v217, v217
	v_exp_f32_e32 v218, v218
	v_pk_fma_f32 v[194:195], v[66:67], s[14:15], v[232:233] op_sel_hi:[1,0,0]
	v_fmac_f32_e32 v181, v177, v205
	v_pk_fma_f32 v[192:193], v[68:69], s[14:15], v[232:233] op_sel_hi:[1,0,0]
	v_pk_fma_f32 v[158:159], v[70:71], s[14:15], v[232:233] op_sel_hi:[1,0,0]
	v_pk_fma_f32 v[154:155], v[72:73], s[14:15], v[232:233] op_sel_hi:[1,0,0]
	v_pk_fma_f32 v[150:151], v[74:75], s[14:15], v[232:233] op_sel_hi:[1,0,0]
	v_pk_fma_f32 v[160:161], v[76:77], s[14:15], v[232:233] op_sel_hi:[1,0,0]
	v_pk_fma_f32 v[156:157], v[78:79], s[14:15], v[232:233] op_sel_hi:[1,0,0]
	v_pk_fma_f32 v[152:153], v[80:81], s[14:15], v[232:233] op_sel_hi:[1,0,0]
	v_fma_f32 v205, v181, v208, v209
	v_add_u32_e32 v179, 16, v179
	s_add_u32 s16, s16, 0x40000
	s_addc_u32 s17, s17, 0
	s_add_u32 s100, s100, 0x40000
	s_addc_u32 s101, s101, 0
	s_cmp_ge_u32 s82, s81
	s_waitcnt lgkmcnt(0)
	s_barrier
	s_cbranch_scc1 .LBB0_1313
	v_mov_b32_e32 v177, v207
	s_branch .LBB0_1299
